# hand-written LayerNorm phase: g/b hoisted out of the row loop, DPP+permlane reductions instead of ds_bpermute, counted waits
# speedup vs baseline: 1.0122x; 1.0113x over previous
; #define TIDX tid_()
; DEVI int wave_() { return __builtin_amdgcn_readfirstlane(tid_() >> 6); }
; DEVI void phase_ln(const Params& p, int l, int which, bool last) {
;     float* hbuf = (float*)(p.ws + OFF_H);
;     bf16_t* hb = (bf16_t*)(p.ws + OFF_HB);
;     float* dst = last ? p.out : hbuf;
;     const float* g = p.ln_g + (size_t)(l * 3 + which) * D_;
;     const float* b = p.ln_b + (size_t)(l * 3 + which) * D_;
;     const int lane = TIDX & 63, wave = wave_();
;     const int stride = gridDim.x * 4;
;     int row = blockIdx.x * 4 + wave;
;     f32x4 nx[4];
;     if (row < T_) {
; #pragma unroll
;         for (int i = 0; i < 4; ++i) nx[i] = *(const f32x4*)(hbuf + (size_t)row * D_ + i * 256 + lane * 4);
;     }
;     for (; row < T_; row += stride) {
;         f32x4 v[4];
; #pragma unroll
;         for (int i = 0; i < 4; ++i) v[i] = nx[i];
;         const int rn = row + stride < T_ ? row + stride : row;
; #pragma unroll
;         for (int i = 0; i < 4; ++i) nx[i] = *(const f32x4*)(hbuf + (size_t)rn * D_ + i * 256 + lane * 4);
.LBB0_722:
	s_load_dword s0, s[18:19], 0x0
	v_readlane_b32 s4, v220, 1
	s_mul_i32 s4, s4, 3
	s_add_i32 s4, s4, s52
	s_lshl_b32 s4, s4, 12
	v_readlane_b32 s38, v222, 0
	v_readlane_b32 s39, v222, 1
	v_readlane_b32 s40, v222, 2
	v_readlane_b32 s41, v222, 3
	s_add_u32 s38, s38, s4
	s_addc_u32 s39, s39, 0
	s_add_u32 s40, s40, s4
	s_addc_u32 s41, s41, 0
	v_and_b32_e32 v60, 63, v133
	v_lshlrev_b32_e32 v61, 4, v60
	v_lshlrev_b32_e32 v62, 3, v60
	v_mov_b32_e32 v63, 0
	global_load_dwordx4 v[64:67], v61, s[38:39]
	global_load_dwordx4 v[68:71], v61, s[38:39] offset:1024
	global_load_dwordx4 v[72:75], v61, s[38:39] offset:2048
	global_load_dwordx4 v[76:79], v61, s[38:39] offset:3072
	global_load_dwordx4 v[80:83], v61, s[40:41]
	global_load_dwordx4 v[84:87], v61, s[40:41] offset:1024
	global_load_dwordx4 v[88:91], v61, s[40:41] offset:2048
	global_load_dwordx4 v[92:95], v61, s[40:41] offset:3072
	v_readfirstlane_b32 s6, v133
	s_nop 1
	s_lshr_b32 s6, s6, 6
	s_lshl_b32 s10, s2, 2
	s_add_i32 s10, s10, s6
	s_add_u32 s42, s8, 0xa218000
	s_addc_u32 s43, s9, 0
	s_add_u32 s44, s8, 0xe218000
	s_addc_u32 s45, s9, 0
	v_readlane_b32 s46, v223, 6
	v_readlane_b32 s47, v223, 7
	s_add_u32 s48, s8, 0x15e1c000
	s_addc_u32 s49, s9, 0
	s_cmp_eq_u32 s74, 52
	s_cselect_b32 s14, 1, 0
	s_waitcnt lgkmcnt(0)
	s_lshl_b32 s11, s0, 2
	s_mov_b32 s15, 0
	s_cmpk_lt_i32 s10, 0x4000
	s_cbranch_scc0 .Lln_done
	s_lshl_b32 s4, s10, 12
	s_add_u32 s24, s42, s4
	s_addc_u32 s25, s43, 0
	global_load_dwordx4 v[18:21], v61, s[24:25]
	global_load_dwordx4 v[22:25], v61, s[24:25] offset:1024
	global_load_dwordx4 v[26:29], v61, s[24:25] offset:2048
	global_load_dwordx4 v[30:33], v61, s[24:25] offset:3072
.Lln_loop:
	s_cmp_eq_u32 s15, 0
	s_cbranch_scc1 .Lln_w0
	s_waitcnt vmcnt(4)
	s_branch .Lln_wd

; DEVI unsigned pk_bf16(float lo, float hi) { const bf16x2n r = __builtin_convertvector((f32x2v){lo, hi}, bf16x2n); return __builtin_bit_cast(unsigned, r); }
; DEVI void phase_ln(const Params& p, int l, int which, bool last) {
;     ...
;     for (; row < T_; row += stride) {
;         f32x4 v[4];
; #pragma unroll
;         for (int i = 0; i < 4; ++i) v[i] = nx[i];
;         const int rn = row + stride < T_ ? row + stride : row;
; #pragma unroll
;         for (int i = 0; i < 4; ++i) nx[i] = *(const f32x4*)(hbuf + (size_t)rn * D_ + i * 256 + lane * 4);
;         float s = 0.f;
; #pragma unroll
;         for (int i = 0; i < 4; ++i) s += (v[i][0] + v[i][1]) + (v[i][2] + v[i][3]);
; #pragma unroll
;         for (int o = 32; o > 0; o >>= 1) s += __shfl_xor(s, o);
;         const float mu = s * (1.0f / 1024.0f);
;         float q = 0.f;
; #pragma unroll
;         for (int i = 0; i < 4; ++i) { const f32x4 d = v[i] - mu; q += (d[0] * d[0] + d[1] * d[1]) + (d[2] * d[2] + d[3] * d[3]); }
; #pragma unroll
;         for (int o = 32; o > 0; o >>= 1) q += __shfl_xor(q, o);
;         const float rstd = rsqrtf(q * (1.0f / 1024.0f) + 1e-5f);
; #pragma unroll
;         for (int i = 0; i < 4; ++i) {
;             const int c0 = i * 256 + lane * 4;
;             const f32x4 gg = *(const f32x4*)(g + c0), bb = *(const f32x4*)(b + c0);
;             const f32x4 o = (v[i] - mu) * rstd * gg + bb;
;             if (last) *(f32x4*)(dst + (size_t)row * D_ + c0) = o;
;             else { u32x2 pk; pk.x = pk_bf16(o[0], o[1]); pk.y = pk_bf16(o[2], o[3]); *(u32x2*)(hb + (size_t)row * D_ + c0) = pk; }
;         }
;         if (!last && lane == 0) ((f32x2v*)(p.ws + OFF_STATS))[row] = (f32x2v){mu, rstd};
;     }
.Lln_wd:
	s_mov_b32 s15, 1
	v_mov_b32_e32 v2, v18
	v_mov_b32_e32 v3, v19
	v_mov_b32_e32 v4, v20
	v_mov_b32_e32 v5, v21
	v_mov_b32_e32 v6, v22
	v_mov_b32_e32 v7, v23
	v_mov_b32_e32 v8, v24
	v_mov_b32_e32 v9, v25
	v_mov_b32_e32 v10, v26
	v_mov_b32_e32 v11, v27
	v_mov_b32_e32 v12, v28
	v_mov_b32_e32 v13, v29
	v_mov_b32_e32 v14, v30
	v_mov_b32_e32 v15, v31
	v_mov_b32_e32 v16, v32
	v_mov_b32_e32 v17, v33
	s_add_i32 s30, s10, s11
	s_cmpk_lt_i32 s30, 0x4000
	s_cbranch_scc0 .Lln_nopf
	s_lshl_b32 s4, s30, 12
	s_add_u32 s24, s42, s4
	s_addc_u32 s25, s43, 0
	global_load_dwordx4 v[18:21], v61, s[24:25]
	global_load_dwordx4 v[22:25], v61, s[24:25] offset:1024
	global_load_dwordx4 v[26:29], v61, s[24:25] offset:2048
	global_load_dwordx4 v[30:33], v61, s[24:25] offset:3072
.Lln_nopf:
	v_add_f32_e32 v36, v2, v3
	v_add_f32_e32 v37, v4, v5
	v_add_f32_e32 v34, v36, v37
	v_add_f32_e32 v36, v6, v7
	v_add_f32_e32 v37, v8, v9
	v_add_f32_e32 v36, v36, v37
	v_add_f32_e32 v34, v34, v36
	v_add_f32_e32 v36, v10, v11
	v_add_f32_e32 v37, v12, v13
	v_add_f32_e32 v36, v36, v37
	v_add_f32_e32 v34, v34, v36
	v_add_f32_e32 v36, v14, v15
	v_add_f32_e32 v37, v16, v17
	v_add_f32_e32 v36, v36, v37
	v_add_f32_e32 v34, v34, v36
	s_nop 1
	v_add_f32_dpp v34, v34, v34 quad_perm:[1,0,3,2] row_mask:0xf bank_mask:0xf
	s_nop 1
	v_add_f32_dpp v34, v34, v34 quad_perm:[2,3,0,1] row_mask:0xf bank_mask:0xf
	s_nop 1
	v_add_f32_dpp v34, v34, v34 row_half_mirror row_mask:0xf bank_mask:0xf
	s_nop 1
	v_add_f32_dpp v34, v34, v34 row_mirror row_mask:0xf bank_mask:0xf
	s_nop 1
	v_mov_b32_e32 v38, v34
	s_nop 1
	v_permlane16_swap_b32_e32 v38, v34
	s_nop 1
	v_add_f32_e32 v34, v38, v34
	v_mov_b32_e32 v38, v34
	s_nop 1
	v_permlane32_swap_b32_e32 v38, v34
	s_nop 1
	v_add_f32_e32 v34, v38, v34
	v_fmac_f32_e32 v2, 0xba800000, v34
	v_fmac_f32_e32 v3, 0xba800000, v34
	v_fmac_f32_e32 v4, 0xba800000, v34
	v_fmac_f32_e32 v5, 0xba800000, v34
	v_fmac_f32_e32 v6, 0xba800000, v34
	v_fmac_f32_e32 v7, 0xba800000, v34
	v_fmac_f32_e32 v8, 0xba800000, v34
	v_fmac_f32_e32 v9, 0xba800000, v34
	v_fmac_f32_e32 v10, 0xba800000, v34
	v_fmac_f32_e32 v11, 0xba800000, v34
	v_fmac_f32_e32 v12, 0xba800000, v34
	v_fmac_f32_e32 v13, 0xba800000, v34
	v_fmac_f32_e32 v14, 0xba800000, v34
	v_fmac_f32_e32 v15, 0xba800000, v34
	v_fmac_f32_e32 v16, 0xba800000, v34
	v_fmac_f32_e32 v17, 0xba800000, v34
	v_mul_f32_e32 v36, v2, v2
	v_fmac_f32_e32 v36, v3, v3
	v_mul_f32_e32 v37, v4, v4
	v_fmac_f32_e32 v37, v5, v5
	v_add_f32_e32 v35, v36, v37
	v_mul_f32_e32 v36, v6, v6
	v_fmac_f32_e32 v36, v7, v7
	v_mul_f32_e32 v37, v8, v8
	v_fmac_f32_e32 v37, v9, v9
	v_add_f32_e32 v36, v36, v37
	v_add_f32_e32 v35, v35, v36
	v_mul_f32_e32 v36, v10, v10
	v_fmac_f32_e32 v36, v11, v11
	v_mul_f32_e32 v37, v12, v12
	v_fmac_f32_e32 v37, v13, v13
	v_add_f32_e32 v36, v36, v37
	v_add_f32_e32 v35, v35, v36
	v_mul_f32_e32 v36, v14, v14
	v_fmac_f32_e32 v36, v15, v15
	v_mul_f32_e32 v37, v16, v16
	v_fmac_f32_e32 v37, v17, v17
	v_add_f32_e32 v36, v36, v37
	v_add_f32_e32 v35, v35, v36
	s_nop 1
	v_add_f32_dpp v35, v35, v35 quad_perm:[1,0,3,2] row_mask:0xf bank_mask:0xf
	s_nop 1
	v_add_f32_dpp v35, v35, v35 quad_perm:[2,3,0,1] row_mask:0xf bank_mask:0xf
	s_nop 1
	v_add_f32_dpp v35, v35, v35 row_half_mirror row_mask:0xf bank_mask:0xf
	s_nop 1
	v_add_f32_dpp v35, v35, v35 row_mirror row_mask:0xf bank_mask:0xf
	s_nop 1
	v_mov_b32_e32 v38, v35
	s_nop 1
	v_permlane16_swap_b32_e32 v38, v35
	s_nop 1
	v_add_f32_e32 v35, v38, v35
	v_mov_b32_e32 v38, v35
	s_nop 1
	v_permlane32_swap_b32_e32 v38, v35
	s_nop 1
	v_add_f32_e32 v35, v38, v35
	v_fmamk_f32 v35, v35, 0x3a800000, v137
	v_rsq_f32_e32 v35, v35
	v_mul_f32_e32 v34, 0x3a800000, v34
	s_nop 0
	v_mul_f32_e32 v2, v2, v35
	v_mul_f32_e32 v3, v3, v35
	v_mul_f32_e32 v4, v4, v35
	v_mul_f32_e32 v5, v5, v35
	v_mul_f32_e32 v6, v6, v35
	v_mul_f32_e32 v7, v7, v35
	v_mul_f32_e32 v8, v8, v35
	v_mul_f32_e32 v9, v9, v35
	v_mul_f32_e32 v10, v10, v35
	v_mul_f32_e32 v11, v11, v35
	v_mul_f32_e32 v12, v12, v35
	v_mul_f32_e32 v13, v13, v35
	v_mul_f32_e32 v14, v14, v35
	v_mul_f32_e32 v15, v15, v35
	v_mul_f32_e32 v16, v16, v35
	v_mul_f32_e32 v17, v17, v35
	v_fma_f32 v2, v64, v2, v80
	v_fma_f32 v3, v65, v3, v81
	v_fma_f32 v4, v66, v4, v82
	v_fma_f32 v5, v67, v5, v83
	v_fma_f32 v6, v68, v6, v84
	v_fma_f32 v7, v69, v7, v85
	v_fma_f32 v8, v70, v8, v86
	v_fma_f32 v9, v71, v9, v87
	v_fma_f32 v10, v72, v10, v88
	v_fma_f32 v11, v73, v11, v89
	v_fma_f32 v12, v74, v12, v90
	v_fma_f32 v13, v75, v13, v91
	v_fma_f32 v14, v76, v14, v92
	v_fma_f32 v15, v77, v15, v93
	v_fma_f32 v16, v78, v16, v94
	v_fma_f32 v17, v79, v17, v95
	s_cmp_eq_u32 s14, 1
	s_cbranch_scc1 .Lln_last
	s_lshl_b32 s4, s10, 11
	s_add_u32 s26, s44, s4
	s_addc_u32 s27, s45, 0
	v_cvt_pk_bf16_f32 v40, v2, v3
	v_cvt_pk_bf16_f32 v41, v4, v5
	global_store_dwordx2 v62, v[40:41], s[26:27]
	v_cvt_pk_bf16_f32 v42, v6, v7
	v_cvt_pk_bf16_f32 v43, v8, v9
	global_store_dwordx2 v62, v[42:43], s[26:27] offset:512
	v_cvt_pk_bf16_f32 v44, v10, v11
	v_cvt_pk_bf16_f32 v45, v12, v13
	global_store_dwordx2 v62, v[44:45], s[26:27] offset:1024
	v_cvt_pk_bf16_f32 v46, v14, v15
	v_cvt_pk_bf16_f32 v47, v16, v17
	global_store_dwordx2 v62, v[46:47], s[26:27] offset:1536
	s_lshl_b32 s4, s10, 3
	s_add_u32 s26, s48, s4
	s_addc_u32 s27, s49, 0
	s_mov_b64 s[30:31], exec
	v_cmp_eq_u32_e32 vcc, 0, v60
	s_and_b64 exec, exec, vcc
	global_store_dwordx2 v63, v[34:35], s[26:27]
	s_mov_b64 exec, s[30:31]
	s_branch .Lln_next
.Lln_last:
	s_lshl_b32 s4, s10, 12
	s_add_u32 s26, s46, s4
	s_addc_u32 s27, s47, 0
	global_store_dwordx4 v61, v[2:5], s[26:27]
	global_store_dwordx4 v61, v[6:9], s[26:27] offset:1024
	global_store_dwordx4 v61, v[10:13], s[26:27] offset:2048
	global_store_dwordx4 v61, v[14:17], s[26:27] offset:3072
.Lln_next:
	s_add_i32 s10, s10, s11
	s_cmpk_lt_i32 s10, 0x4000
	s_cbranch_scc1 .Lln_loop
.Lln_done:
	s_branch .LBB0_743
.LBB0_743:
	s_cbranch_execnz .LBB0_776
